# prep weight transposes: 8 row loads + gain loads of a tile issued together, one wait
# speedup vs baseline: 1.0102x; 1.0067x over previous
; #define LAS __attribute__((address_space(3)))
; __device__ __forceinline__ unsigned pk2(float lo, float hi) { const f32x2_t f = {lo, hi}; const bf16x2_t b = __builtin_convertvector(f, bf16x2_t); return __builtin_bit_cast(unsigned, b); }
; __device__ __forceinline__ void transpose_tile(const float* W, int K, int N, u16* WT, int ldo, const float* g, int tile, LAS float* scr) {
;     ...
;   { const int n = tid >> 3, c = tid & 7; const LAS float* s = scr + (8 * c) * 65 + n;
;     u32x4 o; o.x = pk2(s[0], s[65]); o.y = pk2(s[130], s[195]); o.z = pk2(s[260], s[325]); o.w = pk2(s[390], s[455]);
;     *(u32x4*)(WT + (size_t)(n0 + n) * ldo + k0 + 8 * c) = o; }
;   __syncthreads();
; __device__ __forceinline__ void phase_prep(const Params& P, LAS unsigned char* lds) {
;     ...
;     for (int it = bid; it < NT; it += G) {
;       int r = it; const float* W; int K, N, ldo; size_t off; const float* gg = nullptr;
;       if (r < T_IN) { W = P.in[I_WIN]; K = 1024; N = INW; off = O_WIN; ldo = 1024; gg = P.in[I_GMIX]; }
;       else if ((r -= T_IN) < T_AB) { W = P.in[I_WAB]; K = 512; N = 1024; off = O_WAB; ldo = 512; }
;       else if ((r -= T_AB) < T_HB) { W = P.in[I_WHB]; K = 1024; N = 1024; off = O_WHB; ldo = 1024; }
;       else if ((r -= T_HB) < T_OUT) { W = P.in[I_WOUT]; K = 1024; N = 1024; off = O_WOUT; ldo = 1024; }
;       else if ((r -= T_OUT) < T_F1) { W = P.in[I_WF1]; K = 1024; N = 4096; off = O_WF1; ldo = 1024; gg = P.in[I_GMLP]; }
;       else if ((r -= T_F1) < T_F2) { W = P.in[I_WF2]; K = 4096; N = 1024; off = O_WF2; ldo = 4096; }
;       else { r -= T_F2; W = P.in[I_FW4]; K = 64; N = 4096; off = O_W4; ldo = 256; }
;       transpose_tile(W, K, N, (u16*)(ws + off), ldo, gg, r, scr);
.LBB0_894:
	v_ashrrev_i32_e32 v10, 3, v1
	v_lshlrev_b32_e32 v1, 3, v1
	v_and_b32_e32 v1, 56, v1
	v_mul_u32_u24_e32 v2, 0x104, v1
	v_lshlrev_b32_e32 v3, 2, v10
	v_add3_u32 v6, 0, v2, v3
	s_waitcnt lgkmcnt(0)
	s_barrier
	ds_read2_b32 v[2:3], v6 offset1:65
	ds_read2_b32 v[4:5], v6 offset0:130 offset1:195
	v_add_u32_e32 v8, 0x400, v6
	ds_read2_b32 v[6:7], v8 offset0:4 offset1:69
	ds_read2_b32 v[8:9], v8 offset0:134 offset1:199
	s_add_u32 s0, s4, s8
	s_waitcnt lgkmcnt(3)
	v_cvt_pk_bf16_f32 v2, v2, v3
	s_waitcnt lgkmcnt(2)
	v_cvt_pk_bf16_f32 v3, v4, v5
	s_waitcnt lgkmcnt(1)
	v_cvt_pk_bf16_f32 v4, v6, v7
	v_add_u32_e32 v6, s14, v10
	v_ashrrev_i32_e32 v7, 31, v6
	s_waitcnt lgkmcnt(0)
	v_cvt_pk_bf16_f32 v5, v8, v9
	v_mul_lo_u32 v8, s6, v7
	v_mul_lo_u32 v9, s7, v6
	v_mad_u64_u32 v[6:7], s[6:7], s6, v6, 0
	s_addc_u32 s1, s5, s9
	v_add3_u32 v7, v7, v8, v9
	v_lshl_add_u64 v[6:7], v[6:7], 1, s[0:1]
	s_ashr_i32 s13, s12, 31
	v_readlane_b32 s0, v253, 6
	v_lshl_add_u64 v[6:7], s[12:13], 1, v[6:7]
	v_lshlrev_b32_e32 v80, 1, v1
	s_add_i32 s2, s2, s0
	v_lshl_add_u64 v[6:7], v[6:7], 0, v[80:81]
	s_cmpk_gt_i32 s2, 0x143f
	flat_store_dwordx4 v[6:7], v[2:5]
	s_waitcnt lgkmcnt(0)
	s_barrier
	s_cbranch_scc1 .LBB0_889

; #define LAS __attribute__((address_space(3)))
; #define LAUNDER_V(x) asm volatile("" : "+v"(x))
; __device__ __forceinline__ void transpose_tile(const float* W, int K, int N, u16* WT, int ldo, const float* g, int tile, LAS float* scr) {
;   int tid = threadIdx.x; LAUNDER_V(tid); const int ntn = N / 64, kb = tile / ntn, nb = tile % ntn, k0 = kb * 64, n0 = nb * 64;
; #pragma unroll
;   for (int i = 0; i < 8; ++i) { const int kk = (tid >> 6) + 8 * i, nn = tid & 63; float v = W[(size_t)(k0 + kk) * N + n0 + nn]; if (g) v *= g[k0 + kk]; scr[kk * 65 + nn] = v; }
;   __syncthreads();
.LBB0_918:
	s_lshr_b32 s12, s3, 6
	v_cvt_f32_u32_e32 v1, s12
	s_sub_i32 s16, 0, s12
	s_abs_i32 s15, s14
	s_ashr_i32 s13, s14, 31
	v_rcp_iflag_f32_e32 v2, v1
	v_mov_b32_e32 v1, v215
	v_mul_f32_e32 v2, 0x4f7ffffe, v2
	v_cvt_u32_f32_e32 v2, v2
	v_ashrrev_i32_e32 v8, 6, v1
	v_and_b32_e32 v9, 63, v1
	s_waitcnt lgkmcnt(0)
	v_lshlrev_b32_e32 v80, 2, v9
	v_readfirstlane_b32 s17, v2
	s_mul_i32 s16, s16, s17
	s_mul_hi_u32 s16, s17, s16
	s_add_i32 s17, s17, s16
	s_mul_hi_u32 s16, s15, s17
	s_mul_i32 s17, s16, s12
	s_sub_i32 s15, s15, s17
	s_add_i32 s18, s16, 1
	s_sub_i32 s17, s15, s12
	s_cmp_ge_u32 s15, s12
	s_cselect_b32 s16, s18, s16
	s_cselect_b32 s15, s17, s15
	s_add_i32 s17, s16, 1
	s_cmp_ge_u32 s15, s12
	s_cselect_b32 s15, s17, s16
	s_xor_b32 s15, s15, s13
	s_sub_i32 s13, s15, s13
	s_mul_i32 s15, s13, s12
	s_lshl_b32 s12, s13, 6
	s_sub_i32 s13, s14, s15
	s_lshl_b32 s14, s13, 6
	s_ashr_i32 s15, s14, 31
	s_lshl_b64 s[16:17], s[14:15], 2
	s_add_u32 s0, s0, s16
	s_addc_u32 s1, s1, s17
	v_add_u32_e32 v4, s12, v8
	v_lshl_add_u64 v[2:3], s[0:1], 0, v[80:81]
	v_mad_u64_u32 v[6:7], s[0:1], v4, s3, 0
	v_ashrrev_i32_e32 v5, 31, v4
	v_mov_b32_e32 v10, v7
	v_mad_u64_u32 v[10:11], s[0:1], v5, s3, v[10:11]
	v_mov_b32_e32 v7, v10
	v_lshl_add_u64 v[6:7], v[6:7], 2, v[2:3]
	s_lshl_b32 s15, s3, 5
	v_mov_b32_e32 v100, s15
	v_mov_b32_e32 v101, 0
	v_lshl_add_u64 v[102:103], v[100:101], 0, v[6:7]
	v_lshl_add_u64 v[104:105], v[100:101], 0, v[102:103]
	v_lshl_add_u64 v[106:107], v[100:101], 0, v[104:105]
	v_lshl_add_u64 v[108:109], v[100:101], 0, v[106:107]
	v_lshl_add_u64 v[110:111], v[100:101], 0, v[108:109]
	v_lshl_add_u64 v[112:113], v[100:101], 0, v[110:111]
	v_lshl_add_u64 v[114:115], v[100:101], 0, v[112:113]
	global_load_dword v120, v[6:7], off
	global_load_dword v121, v[102:103], off
	global_load_dword v122, v[104:105], off
	global_load_dword v123, v[106:107], off
	global_load_dword v124, v[108:109], off
	global_load_dword v125, v[110:111], off
	global_load_dword v126, v[112:113], off
	global_load_dword v127, v[114:115], off
	s_cmp_eq_u64 s[10:11], 0
	s_cbranch_scc1 .Ltr_nog
	v_lshl_add_u64 v[116:117], v[4:5], 2, s[10:11]
	global_load_dword v130, v[116:117], off
	global_load_dword v131, v[116:117], off offset:32
	global_load_dword v132, v[116:117], off offset:64
	global_load_dword v133, v[116:117], off offset:96
	global_load_dword v134, v[116:117], off offset:128
	global_load_dword v135, v[116:117], off offset:160
	global_load_dword v136, v[116:117], off offset:192
	global_load_dword v137, v[116:117], off offset:224
	s_waitcnt vmcnt(0)
	v_mul_f32_e32 v120, v120, v130
	v_mul_f32_e32 v121, v121, v131
	v_mul_f32_e32 v122, v122, v132
	v_mul_f32_e32 v123, v123, v133
	v_mul_f32_e32 v124, v124, v134
	v_mul_f32_e32 v125, v125, v135
	v_mul_f32_e32 v126, v126, v136
	v_mul_f32_e32 v127, v127, v137
.Ltr_nog:
	v_lshl_add_u32 v5, v9, 2, 0
	v_mul_u32_u24_e32 v8, 0x104, v8
	v_add_u32_e32 v5, v5, v8
	s_waitcnt vmcnt(0)
	ds_write_b32 v5, v120
	ds_write_b32 v5, v121 offset:2080
	ds_write_b32 v5, v122 offset:4160
	ds_write_b32 v5, v123 offset:6240
	ds_write_b32 v5, v124 offset:8320
	ds_write_b32 v5, v125 offset:10400
	ds_write_b32 v5, v126 offset:12480
	ds_write_b32 v5, v127 offset:14560
	s_branch .LBB0_894
